# masked attention units: context tiles also through the LDS-DMA staged loop (pipelined ctx part bypassed)
# speedup vs baseline: 1.0009x; 1.0009x over previous
; template <bool NOMAX> ...
;     ...
;         { const u32x4 k0 = *(const u32x4*)(kg + (size_t)ATT_TROW(0) * PITCH), k1 = *(const u32x4*)(kg + (size_t)ATT_TROW(1) * PITCH);
;           *(ATT_LAS u32x4*)(ATT_KBUF(0) + koff) = k0; *(ATT_LAS u32x4*)(ATT_KBUF(1) + koff) = k1; }
;         __syncthreads();
;         kreg = *(const u32x4*)(kg + (size_t)ATT_TROW(2) * PITCH); vreg = *(const u32x4*)(vg + (size_t)ATT_TROW(0) * PITCH);
;         ATT_LDK(kf, ATT_KBUF(0));
;         c0 = (f32x16){}; c1 = (f32x16){};
; #pragma unroll
;         for (int d0 = 0; d0 < 4; ++d0) { c0 = __builtin_amdgcn_mfma_f32_32x32x16_bf16(kf[2 * d0], qf[d0], c0, 0, 0, 0); c1 = __builtin_amdgcn_mfma_f32_32x32x16_bf16(kf[2 * d0 + 1], qf[d0], c1, 0, 0, 0); }
;         m = NOMAX ? 0.f : rowmax32(c0, c1);
; #pragma unroll
;         for (int r = 0; r < 16; ++r) { e0[r] = __builtin_amdgcn_exp2f(c0[r] - m); e1[r] = __builtin_amdgcn_exp2f(c1[r] - m); }
; __device__ __forceinline__ void attn_unit(int uv, const float* sink_l, const bf16_t* P, bf16_t* Y, ATT_LAS unsigned char* lds, const float* rpb_l, const float* qn_l, const float* kn_l) {
;     ...
;     int tid = threadIdx.x; asm volatile("" : "+v"(tid)); const int lane = tid & 63, r32 = lane & 31, hi = lane >> 5; const int wid = __builtin_amdgcn_readfirstlane(tid >> 6);
;     const int kkey = 8 * wid + (lane & 7), kc = lane >> 3;
;     const int vkey = 8 * wid + ((lane >> 2) & 1) + 2 * ((lane >> 4) & 3), vd8 = (lane & 3) + 4 * ((lane >> 3) & 1);
;     const int koff = (kc >> 1) * 2048 + (kc & 1) * 1024 + (kkey >> 5) * 512 + (kkey & 31) * 16;
;     const int voff = (vd8 >> 2) * 4096 + (vkey >> 3) * 512 + (vkey & 7) * 64 + (vd8 & 3) * 16;
;     const bf16_t* kg = P + (size_t)kkey * PITCH + a.kcol + kc * 8;
;     const bf16_t* vg = P + (size_t)vkey * PITCH + a.vcol + vd8 * 8;
;     ATT_LAS float* tbl = (ATT_LAS float*)(lds + LDS_TBL);
;     if (a.mode == 2) { for (int i = tid; i < 465; i += 512) tbl[i] = rpb_l[a.hb * 465 + i] * LOG2E; }
;     const int qrow = a.qrow0 + 32 * wid + r32;
;     bf16x8 qf[4];
; #pragma unroll
;     for (int d0 = 0; d0 < 4; ++d0) qf[d0] = *(const bf16x8*)(P + (size_t)qrow * PITCH + a.qcol + 16 * d0 + 8 * hi);
;     const int nlat = a.t_hi - a.t_lo;
;     const int kfrag = hi * 1024 + r32 * 16;
;     const int vlane = ((lane >> 4) & 1) * 32 + (lane & 3) * 8 + (4 * hi + ((lane & 15) >> 2)) * 64;
.LBB0_568:
	v_bfe_u32 v9, v0, 3, 1
	s_lshl_b32 s37, s10, 3
	v_and_b32_e32 v227, 7, v0
	v_lshlrev_b32_e32 v3, 7, v0
	v_lshlrev_b32_e32 v4, 10, v9
	s_movk_i32 s7, 0x1800
	s_lshl_b32 s34, s6, 1
	v_or_b32_e32 v1, s37, v227
	v_and_or_b32 v3, v3, s7, v4
	s_and_b32 s6, s34, 0xfffffe00
	v_lshrrev_b32_e32 v2, 3, v0
	v_add_u32_e32 v3, s6, v3
	v_lshlrev_b32_e32 v4, 4, v1
	s_movk_i32 s6, 0x1f0
	v_bfe_u32 v225, v0, 2, 1
	v_and_b32_e32 v226, 6, v2
	v_and_or_b32 v10, v4, s6, v3
	s_lshl_b32 s6, s10, 9
	v_or_b32_e32 v2, v226, v225
	v_and_b32_e32 v8, 3, v0
	v_lshl_add_u32 v3, v9, 12, s6
	v_readlane_b32 s6, v255, 24
	v_or_b32_e32 v7, s37, v2
	v_lshlrev_b32_e32 v2, 6, v2
	v_lshlrev_b32_e32 v4, 4, v8
	v_readlane_b32 s7, v255, 25
	v_or3_b32 v232, v2, v3, v4
	v_lshlrev_b32_e32 v228, 5, v9
	v_mov_b64_e32 v[2:3], s[6:7]
	v_mad_i64_i32 v[4:5], s[6:7], v1, s65, v[2:3]
	v_and_b32_e32 v1, 56, v0
	v_lshlrev_b32_e32 v229, 3, v8
	v_lshl_add_u64 v[4:5], s[72:73], 1, v[4:5]
	v_lshlrev_b32_e32 v196, 1, v1
	v_mad_i64_i32 v[2:3], s[6:7], v7, s65, v[2:3]
	s_mov_b32 s81, s73
	v_or_b32_e32 v1, v228, v229
	v_lshrrev_b32_e32 v6, 2, v0
	v_lshl_add_u64 v[198:199], v[4:5], 0, v[196:197]
	v_lshl_add_u64 v[2:3], s[80:81], 1, v[2:3]
	v_lshlrev_b32_e32 v196, 1, v1
	v_lshlrev_b32_e32 v219, 2, v224
	v_lshl_add_u64 v[200:201], v[2:3], 0, v[196:197]
	v_lshlrev_b32_e32 v1, 4, v223
	v_lshlrev_b32_e32 v230, 1, v0
	v_and_or_b32 v2, v6, 3, v219
	v_lshl_or_b32 v1, v224, 10, v1
	v_and_b32_e32 v0, 32, v230
	v_lshlrev_b32_e32 v2, 6, v2
	v_or3_b32 v231, v2, v0, v229
	s_andn2_b64 vcc, exec, s[0:1]
	s_mul_i32 s31, s30, 0x1200
	v_add_u32_e32 v220, s35, v10
	v_add_u32_e32 v221, s35, v1
	v_add_u32_e32 v222, s35, v232
	s_cmp_lg_u64 s[4:5], 0
	s_cbranch_scc1 .Lmk_entry
	s_cbranch_vccnz .LBB0_610
	v_mad_u64_u32 v[0:1], s[0:1], s30, v215, v[198:199]
	s_add_i32 s1, s30, 64
	global_load_dwordx4 v[0:3], v[0:1], off
	v_mad_u64_u32 v[4:5], s[2:3], s1, v215, v[198:199]
	global_load_dwordx4 v[4:7], v[4:5], off
	s_add_i32 s0, s30, 0x80
	s_cmp_lt_i32 s29, 2
	s_waitcnt vmcnt(1)
	ds_write_b128 v220, v[0:3]
	s_waitcnt vmcnt(0)
	ds_write_b128 v220, v[4:7] offset:8192
	v_mad_u64_u32 v[0:1], s[2:3], s0, v215, v[198:199]
	s_waitcnt lgkmcnt(0)
	s_barrier
	global_load_dwordx4 v[112:115], v[0:1], off
	v_mad_u64_u32 v[0:1], s[2:3], s30, v215, v[200:201]
	global_load_dwordx4 v[116:119], v[0:1], off
	ds_read_b128 v[0:3], v221
	ds_read_b128 v[4:7], v221 offset:512
	ds_read_b128 v[8:11], v221 offset:2048
	ds_read_b128 v[12:15], v221 offset:2560
	ds_read_b128 v[16:19], v221 offset:4096
	ds_read_b128 v[20:23], v221 offset:4608
	ds_read_b128 v[24:27], v221 offset:6144
	ds_read_b128 v[28:31], v221 offset:6656
	s_waitcnt lgkmcnt(7)
	v_mfma_f32_32x32x16_bf16 v[32:47], v[0:3], v[96:99], 0
	s_waitcnt lgkmcnt(6)
	v_mfma_f32_32x32x16_bf16 v[64:79], v[4:7], v[96:99], 0
	s_waitcnt lgkmcnt(5)
	v_mfma_f32_32x32x16_bf16 v[32:47], v[8:11], v[100:103], v[32:47]
	s_waitcnt lgkmcnt(4)
	v_mfma_f32_32x32x16_bf16 v[64:79], v[12:15], v[100:103], v[64:79]
	s_waitcnt lgkmcnt(3)
	v_mfma_f32_32x32x16_bf16 v[32:47], v[16:19], v[104:107], v[32:47]
	s_waitcnt lgkmcnt(2)
	v_mfma_f32_32x32x16_bf16 v[64:79], v[20:23], v[104:107], v[64:79]
	s_waitcnt lgkmcnt(1)
	v_mfma_f32_32x32x16_bf16 v[32:47], v[24:27], v[108:111], v[32:47]
	s_waitcnt lgkmcnt(0)
	v_mfma_f32_32x32x16_bf16 v[64:79], v[28:31], v[108:111], v[64:79]
	s_nop 9
	v_max_f32_e32 v0, v33, v33
	v_max_f32_e32 v1, v32, v32
	v_max_f32_e32 v0, v1, v0
	v_max3_f32 v1, v34, v35, v65
	v_max3_f32 v0, v0, v64, v66
	v_max3_f32 v0, v0, v67, v36
	v_max3_f32 v1, v1, v38, v39
	v_max3_f32 v0, v0, v37, v68
	v_max3_f32 v1, v1, v70, v71
	v_max3_f32 v0, v0, v69, v40
	v_max3_f32 v1, v1, v42, v43
	v_max3_f32 v0, v0, v41, v72
	v_max3_f32 v1, v1, v74, v75
	v_max3_f32 v0, v0, v73, v44
	v_max3_f32 v1, v1, v46, v47
	v_max3_f32 v0, v0, v45, v76
	v_max3_f32 v1, v1, v78, v79
	v_max3_f32 v0, v0, v77, v1
	v_mov_b32_e32 v1, v0
	s_nop 1
	v_permlane32_swap_b32_e32 v0, v1
	v_max_f32_e32 v1, v1, v1
	v_max_f32_e32 v0, v0, v0
	v_max_f32_e32 v202, v0, v1
	v_sub_f32_e32 v0, v32, v202
	v_exp_f32_e32 v48, v0
	v_sub_f32_e32 v0, v64, v202
	v_exp_f32_e32 v80, v0
	v_sub_f32_e32 v0, v33, v202
	v_exp_f32_e32 v49, v0
	v_sub_f32_e32 v0, v65, v202
	v_exp_f32_e32 v81, v0
	v_sub_f32_e32 v0, v34, v202
	v_exp_f32_e32 v50, v0
	v_sub_f32_e32 v0, v66, v202
	v_exp_f32_e32 v82, v0
	v_sub_f32_e32 v0, v35, v202
	v_exp_f32_e32 v51, v0
	v_sub_f32_e32 v0, v67, v202
	v_exp_f32_e32 v83, v0
	v_sub_f32_e32 v0, v36, v202
	v_exp_f32_e32 v52, v0
	v_sub_f32_e32 v0, v68, v202
	v_exp_f32_e32 v84, v0
	v_sub_f32_e32 v0, v37, v202
	v_exp_f32_e32 v53, v0
	v_sub_f32_e32 v0, v69, v202
	v_exp_f32_e32 v85, v0
	v_sub_f32_e32 v0, v38, v202
	v_exp_f32_e32 v54, v0
	v_sub_f32_e32 v0, v70, v202
	v_exp_f32_e32 v86, v0
	v_sub_f32_e32 v0, v39, v202
	v_exp_f32_e32 v55, v0
	v_sub_f32_e32 v0, v71, v202
	v_exp_f32_e32 v87, v0
	v_sub_f32_e32 v0, v40, v202
	v_exp_f32_e32 v56, v0
	v_sub_f32_e32 v0, v72, v202
	v_exp_f32_e32 v88, v0
	v_sub_f32_e32 v0, v41, v202
	v_exp_f32_e32 v57, v0
	v_sub_f32_e32 v0, v73, v202
	v_exp_f32_e32 v89, v0
	v_sub_f32_e32 v0, v42, v202
	v_exp_f32_e32 v58, v0
	v_sub_f32_e32 v0, v74, v202
	v_exp_f32_e32 v90, v0
	v_sub_f32_e32 v0, v43, v202
	v_exp_f32_e32 v59, v0
	v_sub_f32_e32 v0, v75, v202
	v_exp_f32_e32 v91, v0
	v_sub_f32_e32 v0, v44, v202
	v_exp_f32_e32 v60, v0
	v_sub_f32_e32 v0, v76, v202
	v_exp_f32_e32 v92, v0
	v_sub_f32_e32 v0, v45, v202
	v_exp_f32_e32 v61, v0
	v_sub_f32_e32 v0, v77, v202
	v_exp_f32_e32 v93, v0
	v_sub_f32_e32 v0, v46, v202
	v_exp_f32_e32 v62, v0
	v_sub_f32_e32 v0, v78, v202
	v_exp_f32_e32 v94, v0
	v_sub_f32_e32 v0, v47, v202
	v_exp_f32_e32 v63, v0
	v_sub_f32_e32 v0, v79, v202
	v_exp_f32_e32 v95, v0
	ds_read_b128 v[0:3], v221 offset:8192
	ds_read_b128 v[16:19], v221 offset:8704
	ds_read_b128 v[148:151], v221 offset:10240
	ds_read_b128 v[144:147], v221 offset:10752
	ds_read_b128 v[140:143], v221 offset:12288
	ds_read_b128 v[136:139], v221 offset:12800
	ds_read_b128 v[132:135], v221 offset:14336
	ds_read_b128 v[128:131], v221 offset:14848
	s_waitcnt vmcnt(1)
	ds_write_b128 v220, v[112:115] offset:16384
	s_waitcnt vmcnt(0)
	ds_write_b128 v222, v[116:119] offset:24576
	s_waitcnt lgkmcnt(0)
	s_barrier
	s_cbranch_scc1 .LBB0_608
	s_mul_hi_u32 s3, s1, 0x1200
	s_add_i32 s2, s31, 0x48000
	v_lshl_add_u64 v[4:5], v[200:201], 0, s[2:3]
	s_add_i32 s6, s30, 0xc0
	v_mad_u64_u32 v[6:7], s[2:3], s6, v215, v[198:199]
	global_load_dwordx4 v[124:127], v[4:5], off
	global_load_dwordx4 v[120:123], v[6:7], off
	s_cmp_gt_u32 s29, 3
	s_cselect_b64 s[8:9], -1, 0
	s_cmp_lt_u32 s29, 4
	s_cbranch_scc1 .LBB0_572
	s_waitcnt vmcnt(0)
	ds_write_b128 v220, v[120:123]

; #define ATT_LAS __attribute__((address_space(3)))
; __device__ __forceinline__ void attn_unit(int uv, const float* sink_l, const bf16_t* P, bf16_t* Y, ATT_LAS unsigned char* lds, const float* rpb_l, const float* qn_l, const float* kn_l) {
;     ...
;     float m, lsum = 0.f; f32x16 o0 = {}, o1 = {};
;     {
;         const int NF = 4 + (a.mode == 0 ? nlat : 0);
;         bool nomax = false;
;         if (uv < 512) {
;             float gq = __builtin_fabsf(qn_l[lane]), gk = __builtin_fabsf(kn_l[lane]);
; #pragma unroll
;             for (int o = 1; o < 64; o <<= 1) { gq = __builtin_fmaxf(gq, __shfl_xor(gq, o)); gk = __builtin_fmaxf(gk, __shfl_xor(gk, o)); }
;             nomax = __builtin_amdgcn_readfirstlane(__float_as_int(gq * gk * (8.0f * LOG2E))) < __float_as_int(40.0f);
;         }
;         if (nomax) pipe_tiles<true>(a, NF, kg, vg, qf, lds, koff, voff, kfrag, vlane, m, lsum, o0, o1);
;         else       pipe_tiles<false>(a, NF, kg, vg, qf, lds, koff, voff, kfrag, vlane, m, lsum, o0, o1);
;     }
;     if (a.mode != 0 && nlat > 0) {
;         u32x4 kreg, vreg;
;         { const size_t ro = (size_t)ATT_TROW(4) * PITCH; kreg = *(const u32x4*)(kg + ro); vreg = *(const u32x4*)(vg + ro); }
;         *(ATT_LAS u32x4*)(ATT_KBUF(0) + koff) = kreg; *(ATT_LAS u32x4*)(ATT_VBUF(0) + voff) = vreg;
.Lmk_entry:
	v_mov_b32_e32 v202, v216
	v_mov_b32_e32 v124, 0
	v_mov_b32_e32 v0, 0
	v_mov_b32_e32 v1, 0
	v_mov_b32_e32 v2, 0
	v_mov_b32_e32 v3, 0
	v_mov_b32_e32 v4, 0
	v_mov_b32_e32 v5, 0
	v_mov_b32_e32 v6, 0
	v_mov_b32_e32 v7, 0
	v_mov_b32_e32 v8, 0
	v_mov_b32_e32 v9, 0
	v_mov_b32_e32 v10, 0
	v_mov_b32_e32 v11, 0
	v_mov_b32_e32 v12, 0
	v_mov_b32_e32 v13, 0
	v_mov_b32_e32 v14, 0
	v_mov_b32_e32 v15, 0
	v_mov_b32_e32 v16, 0
	v_mov_b32_e32 v17, 0
	v_mov_b32_e32 v18, 0
	v_mov_b32_e32 v19, 0
	v_mov_b32_e32 v20, 0
	v_mov_b32_e32 v21, 0
	v_mov_b32_e32 v22, 0
	v_mov_b32_e32 v23, 0
	v_mov_b32_e32 v24, 0
	v_mov_b32_e32 v25, 0
	v_mov_b32_e32 v26, 0
	v_mov_b32_e32 v27, 0
	v_mov_b32_e32 v28, 0
	v_mov_b32_e32 v29, 0
	v_mov_b32_e32 v30, 0
	v_mov_b32_e32 v31, 0
	s_xor_b64 s[2:3], s[24:25], -1
	s_branch .Lmk_pre
.Lmk_pre:
	s_lshl_b32 s92, s93, 6
	s_add_i32 s84, s27, s92
	v_lshrrev_b32_e32 v116, 6, v192
	v_and_b32_e32 v117, 63, v192
	v_lshrrev_b32_e32 v118, 3, v117
	v_sub_u32_e32 v118, v118, v116
	v_mul_i32_i24_e32 v244, 0x8ff0, v118
	v_ashrrev_i32_e32 v245, 31, v244
	v_and_b32_e32 v118, 3, v116
	v_lshlrev_b32_e32 v118, 4, v118
	v_lshlrev_b32_e32 v119, 3, v116
	v_sub_u32_e32 v118, v118, v119
	v_bfe_u32 v119, v117, 3, 1
	v_bfe_u32 v204, v117, 4, 1
	v_bfe_u32 v205, v117, 5, 1
	v_add_u32_e32 v208, v119, v204
	v_lshl_add_u32 v208, v205, 1, v208
	v_lshl_add_u32 v118, v208, 1, v118
	v_lshrrev_b32_e32 v209, 2, v116
	v_sub_u32_e32 v209, v209, v119
	v_mul_i32_i24_e32 v118, 0x1200, v118
	v_lshl_add_u32 v246, v209, 6, v118
	v_ashrrev_i32_e32 v247, 31, v246
	v_readfirstlane_b32 s100, v116
	s_mov_b64 s[98:99], 0x48000
	s_lshl_b32 s100, s100, 10
	v_mad_i64_i32 v[116:117], s[0:1], s84, v215, v[198:199]
	v_mad_i64_i32 v[118:119], s[0:1], s84, v215, v[200:201]
	v_lshl_add_u64 v[116:117], v[244:245], 0, v[116:117]
	v_lshl_add_u64 v[118:119], v[246:247], 0, v[118:119]
	v_mad_i64_i32 v[112:113], s[0:1], s30, v215, v[198:199]
	v_mad_i64_i32 v[114:115], s[0:1], s30, v215, v[200:201]
	v_lshl_add_u64 v[112:113], v[244:245], 0, v[112:113]
	v_lshl_add_u64 v[114:115], v[246:247], 0, v[114:115]
	s_mov_b32 m0, s100
	s_nop 0
	global_load_lds_dwordx4 v[112:113], off
	s_add_i32 s101, s100, 0x6000
	s_mov_b32 m0, s101
	s_nop 0
	global_load_lds_dwordx4 v[114:115], off
	v_lshl_add_u64 v[112:113], v[112:113], 0, s[98:99]
	v_lshl_add_u64 v[114:115], v[114:115], 0, s[98:99]
	s_add_i32 s101, s100, 0x2000
	s_mov_b32 m0, s101
	s_nop 0
	global_load_lds_dwordx4 v[112:113], off
	s_add_i32 s101, s100, 0x8000
	s_mov_b32 m0, s101
	s_nop 0
	global_load_lds_dwordx4 v[114:115], off
	v_lshl_add_u64 v[112:113], v[112:113], 0, s[98:99]
	v_lshl_add_u64 v[114:115], v[114:115], 0, s[98:99]
	v_and_or_b32 v32, s28, 32, v223
	v_subrev_co_u32_e32 v32, vcc, 8, v32
	v_min_u32_e32 v32, 48, v32
	v_or_b32_e32 v33, 32, v219
	v_cndmask_b32_e64 v32, v32, 0, vcc
	v_or_b32_e32 v50, 17, v219
	v_sub_u32_e32 v33, v33, v32
	v_or_b32_e32 v51, 49, v219
	v_cmp_gt_u32_e64 s[68:69], 16, v33
	v_sub_u32_e32 v33, v50, v32
	v_or_b32_e32 v34, 1, v219
	v_cmp_gt_u32_e64 s[40:41], 16, v33
	v_sub_u32_e32 v33, v51, v32
	v_sub_u32_e32 v34, v34, v32
	v_cmp_gt_u32_e64 s[42:43], 16, v33
	v_or_b32_e32 v33, 18, v219
	v_cmp_gt_u32_e64 s[4:5], 16, v34
	v_or_b32_e32 v34, 50, v219
	v_sub_u32_e32 v33, v33, v32
	v_cmp_gt_u32_e64 s[44:45], 16, v33
	v_sub_u32_e32 v33, v34, v32
	v_cmp_gt_u32_e64 s[46:47], 16, v33
	v_or_b32_e32 v33, 19, v219
	v_or_b32_e32 v34, 51, v219
	v_sub_u32_e32 v33, v33, v32
	v_cmp_gt_u32_e64 s[48:49], 16, v33
	v_sub_u32_e32 v33, v34, v32
	v_cmp_gt_u32_e64 s[50:51], 16, v33
	v_or_b32_e32 v33, 24, v219
	v_or_b32_e32 v34, 56, v219
	v_sub_u32_e32 v33, v33, v32
	v_cmp_gt_u32_e64 s[52:53], 16, v33
	v_sub_u32_e32 v33, v34, v32
	s_add_i32 s85, s28, s26
	v_cmp_gt_u32_e64 s[54:55], 16, v33
	v_or_b32_e32 v33, 25, v219
	s_ashr_i32 s82, s85, 6
	v_or_b32_e32 v34, 57, v219
	v_sub_u32_e32 v33, v33, v32
	s_add_i32 s0, s82, -4
	v_cmp_gt_u32_e64 s[56:57], 16, v33
	v_sub_u32_e32 v33, v34, v32
	s_min_u32 s0, s0, 0x78
	v_cmp_gt_u32_e64 s[58:59], 16, v33
	v_or_b32_e32 v33, 26, v219
	s_cmp_gt_i32 s82, 3
	v_or_b32_e32 v34, 58, v219
	v_sub_u32_e32 v33, v33, v32
	s_cselect_b32 s79, s0, 0
	v_cmp_gt_u32_e64 s[60:61], 16, v33
	v_sub_u32_e32 v33, v34, v32
; #define ATT_LAS __attribute__((address_space(3)))
; __device__ __forceinline__ int crow(int r, int hi) { return (r & 3) + 8 * (r >> 2) + 4 * hi; }
; __device__ __forceinline__ void attn_unit(int uv, const float* sink_l, const bf16_t* P, bf16_t* Y, ATT_LAS unsigned char* lds, const float* rpb_l, const float* qn_l, const float* kn_l) {
;     ...
;     if (a.mode != 0 && nlat > 0) {
;         u32x4 kreg, vreg;
;         { const size_t ro = (size_t)ATT_TROW(4) * PITCH; kreg = *(const u32x4*)(kg + ro); vreg = *(const u32x4*)(vg + ro); }
;         *(ATT_LAS u32x4*)(ATT_KBUF(0) + koff) = kreg; *(ATT_LAS u32x4*)(ATT_VBUF(0) + voff) = vreg;
;         __syncthreads();
;         const int qw = a.qpos0 + 32 * wid, qr = qw >> 6;
;         for (int t = 0; t < nlat; ++t) {
;             const int cur = t & 1, tl = a.t_lo + t;
;             if (t + 1 < nlat) { const size_t ro = (size_t)ATT_TROW(t + 5) * PITCH; kreg = *(const u32x4*)(kg + ro); vreg = *(const u32x4*)(vg + ro); }
;             bool need;
;             if (a.mode == 1) need = (tl * 64 + 63 >= qw - 128) && (tl * 64 <= qw + 31 + 128);
;             else { const int rs = clampi(qr - 4, 0, 120); need = (tl >= rs) && (tl < rs + 8); }
;     ...
;                 else { const int qc = 32 * (wid & 1) + r32, cs = clampi(qc - 8, 0, 48); const ATT_LAS float* trow = tbl + (tl - qr + 7) * 31 + 15 - qc;
; #pragma unroll
;                     for (int r = 0; r < 16; ++r) { const int kcl = crow(r, hi);
;                         const float b0 = trow[kcl], b1 = trow[kcl + 32];
;                         p0[r] = ((unsigned)(kcl - cs) < 16u) ? p0[r] + b0 : NEGF;
;                         p1[r] = ((unsigned)(kcl + 32 - cs) < 16u) ? p1[r] + b1 : NEGF; } }
	v_or_b32_e32 v35, 33, v219
	v_or_b32_e32 v36, 2, v219
	v_or_b32_e32 v37, 34, v219
	v_or_b32_e32 v38, 3, v219
	v_or_b32_e32 v39, 35, v219
	v_or_b32_e32 v40, 8, v219
	v_or_b32_e32 v41, 40, v219
	v_or_b32_e32 v42, 9, v219
	v_or_b32_e32 v43, 41, v219
	v_or_b32_e32 v44, 10, v219
	v_or_b32_e32 v45, 42, v219
	v_or_b32_e32 v46, 11, v219
	v_or_b32_e32 v47, 43, v219
	v_or_b32_e32 v48, 16, v219
	v_or_b32_e32 v49, 48, v219
	s_add_i32 s33, s85, 0xffffff80
	s_add_i32 s91, s85, 0x9f
	s_add_i32 s6, s79, 8
	v_cmp_gt_u32_e64 s[62:63], 16, v33
	v_or_b32_e32 v33, 27, v219
	v_or_b32_e32 v34, 59, v219
	s_lshl_b64 s[66:67], s[72:73], 1
	v_readlane_b32 vcc_lo, v255, 29
	v_sub_u32_e32 v52, v219, v32
	v_sub_u32_e32 v35, v35, v32
	v_sub_u32_e32 v36, v36, v32
	v_sub_u32_e32 v37, v37, v32
	v_sub_u32_e32 v38, v38, v32
	v_sub_u32_e32 v39, v39, v32
	v_sub_u32_e32 v40, v40, v32
	v_sub_u32_e32 v41, v41, v32
	v_sub_u32_e32 v42, v42, v32
	v_sub_u32_e32 v43, v43, v32
	v_sub_u32_e32 v44, v44, v32
	v_sub_u32_e32 v45, v45, v32
	v_sub_u32_e32 v46, v46, v32
	v_sub_u32_e32 v47, v47, v32
	v_sub_u32_e32 v48, v48, v32
	v_sub_u32_e32 v49, v49, v32
	v_sub_u32_e32 v33, v33, v32
	v_sub_u32_e32 v32, v34, v32
	v_readlane_b32 vcc_hi, v255, 30
	s_add_u32 s86, vcc_lo, s66
	s_movk_i32 s83, 0x1200
	s_addc_u32 s87, vcc_hi, s67
	v_cmp_gt_u32_e64 s[66:67], 16, v32
	v_add_u32_e32 v32, s37, v227
	v_cmp_gt_u32_e64 s[64:65], 16, v33
	v_mad_i64_i32 v[32:33], s[96:97], v32, s83, 0
	v_mad_i64_i32 v[32:33], s[96:97], s84, v215, v[32:33]
	s_movk_i32 s72, 0x70
	v_and_or_b32 v32, v230, s72, v32
	s_mul_hi_i32 s72, s84, 0x1200
	s_mulk_i32 s84, 0x1200
	s_lshl_b64 s[80:81], s[80:81], 1
	s_add_u32 s80, s80, s84
	s_addc_u32 s81, s81, s72
	v_lshl_add_u64 v[120:121], s[86:87], 0, v[32:33]
	v_add3_u32 v34, s37, v226, v225
	v_mov_b64_e32 v[32:33], s[80:81]
	v_mad_i64_i32 v[32:33], s[80:81], v34, s83, v[32:33]
	v_add_lshl_u32 v196, v228, v229, 1
	v_lshl_add_u64 v[32:33], v[32:33], 0, v[196:197]
	v_lshl_add_u64 v[122:123], vcc, 0, v[32:33]
	v_add_u32_e32 v32, s85, v223
	s_mul_i32 s72, s93, 0x7c
	v_sub_u32_e32 v126, v219, v32
	v_lshl_add_u32 v32, v224, 4, s72
	v_lshlrev_b32_e32 v33, 2, v223
	v_sub_u32_e32 v32, v32, v33
	s_mulk_i32 s82, 0x7c
	v_subrev_u32_e32 v32, s82, v32
	s_and_b32 s72, s34, 0x80
	v_subrev_u32_e32 v32, s72, v32
	v_readlane_b32 s72, v255, 31
	v_add_u32_e32 v125, s35, v231
	s_mov_b32 s7, 0
	v_cmp_gt_u32_e64 s[0:1], 16, v52
	v_cmp_gt_u32_e64 s[8:9], 16, v35
	v_cmp_gt_u32_e64 s[10:11], 16, v36
	v_cmp_gt_u32_e64 s[12:13], 16, v37
	v_cmp_gt_u32_e64 s[14:15], 16, v38
	v_cmp_gt_u32_e64 s[16:17], 16, v39
	v_cmp_gt_u32_e64 s[18:19], 16, v40
	v_cmp_gt_u32_e64 s[20:21], 16, v41
	v_cmp_gt_u32_e64 s[22:23], 16, v42
	v_cmp_gt_u32_e64 s[24:25], 16, v43
	v_cmp_gt_u32_e64 s[26:27], 16, v44
	v_cmp_gt_u32_e64 s[28:29], 16, v45
	v_cmp_gt_u32_e64 s[30:31], 16, v46
	v_cmp_gt_u32_e64 s[94:95], 16, v47
	v_cmp_gt_u32_e64 s[76:77], 16, v48
	v_cmp_gt_u32_e64 s[38:39], 16, v49
	v_add_u32_e32 v127, s72, v32
	s_mov_b32 s32, 0
	s_sub_i32 s93, s93, 4
	s_sub_i32 s92, s92, 0x100
	v_subrev_u32_e32 v127, 0x1f0, v127
	s_add_i32 s71, s71, 4
	s_waitcnt vmcnt(2)
	s_waitcnt lgkmcnt(0)
	s_barrier
.Lmk_top:
	s_add_i32 s96, s7, 2
	s_cmp_lt_i32 s96, s71
	s_cselect_b64 s[82:83], -1, 0
	s_cbranch_scc0 .Lmk_nodma
	s_cmp_eq_u32 s96, 4
	s_cbranch_scc0 .Lmk_noswitch
	v_mov_b32_e32 v112, v116
	v_mov_b32_e32 v113, v117
	v_mov_b32_e32 v114, v118
	v_mov_b32_e32 v115, v119
.Lmk_noswitch:
	s_add_i32 s80, s32, 2
	s_cmp_ge_u32 s80, 3
	s_cselect_b32 s81, 3, 0
	s_sub_i32 s80, s80, s81
	s_lshl_b32 s81, s80, 13
	s_add_i32 s96, s81, 0x6000
	s_cmp_eq_u32 s80, 2
	s_cselect_b32 s80, 0xc000, s96
	s_add_i32 s81, s81, s100
	s_mov_b32 m0, s81
	s_nop 0
	global_load_lds_dwordx4 v[112:113], off
	s_add_i32 s80, s80, s100
	s_mov_b32 m0, s80
	s_nop 0
	global_load_lds_dwordx4 v[114:115], off
	v_lshl_add_u64 v[112:113], v[112:113], 0, s[98:99]
	v_lshl_add_u64 v[114:115], v[114:115], 0, s[98:99]
.Lmk_nodma:
	s_cmp_lt_i32 s7, 4
	s_cbranch_scc1 .LBB0_657
	s_and_b64 vcc, exec, s[2:3]
	s_cbranch_vccz .Lmk_need_win
	s_add_i32 s72, s93, s7
	s_cmp_ge_i32 s72, s79
	s_cbranch_scc0 .Lmsk_tail
	s_cmp_lt_i32 s72, s6
	s_cbranch_scc0 .Lmsk_tail
	s_branch .LBB0_657

; #define ATT_LAS __attribute__((address_space(3)))
; __device__ __forceinline__ int crow(int r, int hi) { return (r & 3) + 8 * (r >> 2) + 4 * hi; }
; __device__ __forceinline__ void attn_unit(int uv, const float* sink_l, const bf16_t* P, bf16_t* Y, ATT_LAS unsigned char* lds, const float* rpb_l, const float* qn_l, const float* kn_l) {
;     ...
;                 const ATT_LAS unsigned char* Kb = ATT_KBUF(cur); const ATT_LAS unsigned char* Vb = ATT_VBUF(cur);
;                 f32x16 p0 = {}, p1 = {};
; #pragma unroll
;                 for (int d0 = 0; d0 < 4; ++d0) {
;                     const bf16x8 k0 = *(const ATT_LAS bf16x8*)(Kb + kfrag + d0 * 2048);
;                     const bf16x8 k1 = *(const ATT_LAS bf16x8*)(Kb + kfrag + d0 * 2048 + 512);
;                     p0 = __builtin_amdgcn_mfma_f32_32x32x16_bf16(k0, qf[d0], p0, 0, 0, 0);
;                     p1 = __builtin_amdgcn_mfma_f32_32x32x16_bf16(k1, qf[d0], p1, 0, 0, 0);
;                 }
;                 if (a.mode == 1) { const int dq = tl * 64 - (qw + r32);
; #pragma unroll
;                     for (int r = 0; r < 16; ++r) { const int d = dq + crow(r, hi); if (d > 128 || d < -128) p0[r] = NEGF; if (d + 32 > 128 || d + 32 < -128) p1[r] = NEGF; } }
;                 else { const int qc = 32 * (wid & 1) + r32, cs = clampi(qc - 8, 0, 48); const ATT_LAS float* trow = tbl + (tl - qr + 7) * 31 + 15 - qc;
; #pragma unroll
;                     for (int r = 0; r < 16; ++r) { const int kcl = crow(r, hi);
;                         const float b0 = trow[kcl], b1 = trow[kcl + 32];
;                         p0[r] = ((unsigned)(kcl - cs) < 16u) ? p0[r] + b0 : NEGF;
;                         p1[r] = ((unsigned)(kcl + 32 - cs) < 16u) ? p1[r] + b1 : NEGF; } }
;                 const float mt = rowmax32(p0, p1);
;                 if (__any(mt > m)) { const float mn = fmaxf(m, mt), alpha = __builtin_amdgcn_exp2f(m - mn); m = mn; lsum *= alpha;
; #pragma unroll
;                     for (int r = 0; r < 16; ++r) { o0[r] *= alpha; o1[r] *= alpha; } }
;                 float sum = 0.f;
; #pragma unroll
;                 for (int r = 0; r < 16; ++r) { p0[r] = __builtin_amdgcn_exp2f(p0[r] - m); p1[r] = __builtin_amdgcn_exp2f(p1[r] - m); sum += p0[r] + p1[r]; }
.LBB0_657:
	s_lshl_b32 s86, s32, 13
	s_cmp_eq_u32 s32, 2
	s_cselect_b32 s87, 0x6000, s86
	v_add_u32_e32 v40, s86, v221
	v_add_u32_e32 v242, s87, v125
	ds_read_b128 v[128:131], v40
	ds_read_b128 v[132:135], v40 offset:512
	ds_read_b128 v[136:139], v40 offset:2048
	ds_read_b128 v[140:143], v40 offset:2560
	ds_read_b128 v[144:147], v40 offset:4096
	ds_read_b128 v[148:151], v40 offset:4608
	ds_read_b128 v[152:155], v40 offset:6144
	ds_read_b128 v[156:159], v40 offset:6656
	s_cmp_lt_i32 s7, 4
	s_cbranch_scc0 .Lmk_lat
	ds_read_b64_tr_b16 v[160:161], v242 offset:24576
	ds_read_b64_tr_b16 v[162:163], v242 offset:25088
	ds_read_b64_tr_b16 v[176:177], v242 offset:28672
	ds_read_b64_tr_b16 v[178:179], v242 offset:29184
	ds_read_b64_tr_b16 v[164:165], v242 offset:25600
	ds_read_b64_tr_b16 v[166:167], v242 offset:26112
	ds_read_b64_tr_b16 v[180:181], v242 offset:29696
	s_waitcnt lgkmcnt(14)
	v_mfma_f32_32x32x16_bf16 v[80:95], v[128:131], v[96:99], 0
	ds_read_b64_tr_b16 v[182:183], v242 offset:30208
	s_waitcnt lgkmcnt(14)
	v_mfma_f32_32x32x16_bf16 v[48:63], v[132:135], v[96:99], 0
	ds_read_b64_tr_b16 v[168:169], v242 offset:26624
	s_waitcnt lgkmcnt(14)
	v_mfma_f32_32x32x16_bf16 v[80:95], v[136:139], v[100:103], v[80:95]
	ds_read_b64_tr_b16 v[170:171], v242 offset:27136
	s_waitcnt lgkmcnt(14)
	v_mfma_f32_32x32x16_bf16 v[48:63], v[140:143], v[100:103], v[48:63]
	ds_read_b64_tr_b16 v[184:185], v242 offset:30720
	s_waitcnt lgkmcnt(14)
	v_mfma_f32_32x32x16_bf16 v[80:95], v[144:147], v[104:107], v[80:95]
	ds_read_b64_tr_b16 v[186:187], v242 offset:31232
	s_waitcnt lgkmcnt(14)
	v_mfma_f32_32x32x16_bf16 v[48:63], v[148:151], v[104:107], v[48:63]
	ds_read_b64_tr_b16 v[172:173], v242 offset:27648
	s_waitcnt lgkmcnt(14)
	v_mfma_f32_32x32x16_bf16 v[80:95], v[152:155], v[108:111], v[80:95]
	ds_read_b64_tr_b16 v[174:175], v242 offset:28160
	s_waitcnt lgkmcnt(14)
	v_mfma_f32_32x32x16_bf16 v[48:63], v[156:159], v[108:111], v[48:63]
	ds_read_b64_tr_b16 v[188:189], v242 offset:31744
	s_waitcnt lgkmcnt(14)
	ds_read_b64_tr_b16 v[190:191], v242 offset:32256
	s_nop 7
	s_nop 0
	v_max3_f32 v204, v80, v81, v82
	v_max3_f32 v205, v83, v84, v85
	v_max3_f32 v204, v204, v86, v87
	v_max3_f32 v205, v205, v88, v89
	v_max3_f32 v204, v204, v90, v91
	v_max3_f32 v205, v205, v92, v93
	v_max3_f32 v204, v204, v94, v95
	v_max3_f32 v205, v205, v48, v49
	v_max3_f32 v204, v204, v50, v51
	v_max3_f32 v205, v205, v52, v53
	v_max3_f32 v204, v204, v54, v55
	v_max3_f32 v205, v205, v56, v57
	v_max3_f32 v204, v204, v58, v59
	v_max3_f32 v205, v205, v60, v61
	v_max3_f32 v204, v204, v62, v63
	v_max_f32_e32 v204, v204, v205
	v_mov_b32_e32 v205, v204
	s_nop 1
	v_permlane32_swap_b32_e32 v204, v205
	v_max_f32_e32 v204, v204, v205
	v_cmp_gt_f32_e32 vcc, v204, v202
	s_cbranch_vccz .Lnb_ctx_norescale
	v_max_f32_e32 v205, v202, v204
	v_sub_f32_e32 v208, v202, v205
	v_exp_f32_e32 v208, v208
	v_mov_b32_e32 v202, v205
	v_pk_mul_f32 v[0:1], v[0:1], v[208:209] op_sel_hi:[1,0]
	v_pk_mul_f32 v[2:3], v[2:3], v[208:209] op_sel_hi:[1,0]
	v_pk_mul_f32 v[4:5], v[4:5], v[208:209] op_sel_hi:[1,0]
	v_pk_mul_f32 v[6:7], v[6:7], v[208:209] op_sel_hi:[1,0]
	v_pk_mul_f32 v[8:9], v[8:9], v[208:209] op_sel_hi:[1,0]
	v_pk_mul_f32 v[10:11], v[10:11], v[208:209] op_sel_hi:[1,0]
	v_pk_mul_f32 v[12:13], v[12:13], v[208:209] op_sel_hi:[1,0]
	v_pk_mul_f32 v[14:15], v[14:15], v[208:209] op_sel_hi:[1,0]
	v_pk_mul_f32 v[16:17], v[16:17], v[208:209] op_sel_hi:[1,0]
	v_pk_mul_f32 v[18:19], v[18:19], v[208:209] op_sel_hi:[1,0]
	v_pk_mul_f32 v[20:21], v[20:21], v[208:209] op_sel_hi:[1,0]
	v_pk_mul_f32 v[22:23], v[22:23], v[208:209] op_sel_hi:[1,0]
	v_pk_mul_f32 v[24:25], v[24:25], v[208:209] op_sel_hi:[1,0]
	v_pk_mul_f32 v[26:27], v[26:27], v[208:209] op_sel_hi:[1,0]
	v_pk_mul_f32 v[28:29], v[28:29], v[208:209] op_sel_hi:[1,0]
	v_pk_mul_f32 v[30:31], v[30:31], v[208:209] op_sel_hi:[1,0]
	v_mul_f32_e32 v124, v124, v208
.Lnb_ctx_norescale:
	v_sub_f32_e32 v80, v80, v202
	v_sub_f32_e32 v81, v81, v202
	v_sub_f32_e32 v82, v82, v202
	v_sub_f32_e32 v83, v83, v202
	v_sub_f32_e32 v84, v84, v202
	v_sub_f32_e32 v85, v85, v202
	v_sub_f32_e32 v86, v86, v202
	v_sub_f32_e32 v87, v87, v202
	v_sub_f32_e32 v88, v88, v202
	v_sub_f32_e32 v89, v89, v202
	v_sub_f32_e32 v90, v90, v202
	v_sub_f32_e32 v91, v91, v202
	v_sub_f32_e32 v92, v92, v202
	v_sub_f32_e32 v93, v93, v202
	v_sub_f32_e32 v94, v94, v202
	v_sub_f32_e32 v95, v95, v202
	v_sub_f32_e32 v48, v48, v202
	v_sub_f32_e32 v49, v49, v202
	v_sub_f32_e32 v50, v50, v202
	v_sub_f32_e32 v51, v51, v202
	v_sub_f32_e32 v52, v52, v202
	v_sub_f32_e32 v53, v53, v202
	v_sub_f32_e32 v54, v54, v202
	v_sub_f32_e32 v55, v55, v202
	v_sub_f32_e32 v56, v56, v202
	v_sub_f32_e32 v57, v57, v202
	v_sub_f32_e32 v58, v58, v202
	v_sub_f32_e32 v59, v59, v202
	v_sub_f32_e32 v60, v60, v202
	v_sub_f32_e32 v61, v61, v202
	v_sub_f32_e32 v62, v62, v202
	v_sub_f32_e32 v63, v63, v202
	v_exp_f32_e32 v80, v80
	v_exp_f32_e32 v81, v81
	v_exp_f32_e32 v82, v82
	v_exp_f32_e32 v83, v83
	v_exp_f32_e32 v84, v84
	v_exp_f32_e32 v85, v85
	v_exp_f32_e32 v86, v86
	v_exp_f32_e32 v87, v87
	v_exp_f32_e32 v88, v88
	v_exp_f32_e32 v89, v89
	v_exp_f32_e32 v90, v90
	v_exp_f32_e32 v91, v91
	v_exp_f32_e32 v92, v92
	v_exp_f32_e32 v93, v93
	v_exp_f32_e32 v94, v94
	v_exp_f32_e32 v95, v95
	v_exp_f32_e32 v48, v48
	v_exp_f32_e32 v49, v49
	v_exp_f32_e32 v50, v50
	v_exp_f32_e32 v51, v51
	v_exp_f32_e32 v52, v52
	v_exp_f32_e32 v53, v53
	v_exp_f32_e32 v54, v54
	v_exp_f32_e32 v55, v55
	v_exp_f32_e32 v56, v56
	v_exp_f32_e32 v57, v57
	v_exp_f32_e32 v58, v58
	v_exp_f32_e32 v59, v59
	v_exp_f32_e32 v60, v60
	v_exp_f32_e32 v61, v61
	v_exp_f32_e32 v62, v62
	v_exp_f32_e32 v63, v63
; #define ATT_LAS __attribute__((address_space(3)))
; __device__ __forceinline__ unsigned pk_bf16(float lo, float hi) { unsigned r; asm volatile("v_cvt_pk_bf16_f32 %0, %1, %2" : "=v"(r) : "v"(lo), "v"(hi)); return r; }
; __device__ __forceinline__ void attn_unit(int uv, const float* sink_l, const bf16_t* P, bf16_t* Y, ATT_LAS unsigned char* lds, const float* rpb_l, const float* qn_l, const float* kn_l) {
;     ...
;                 float sum = 0.f;
; #pragma unroll
;                 for (int r = 0; r < 16; ++r) { p0[r] = __builtin_amdgcn_exp2f(p0[r] - m); p1[r] = __builtin_amdgcn_exp2f(p1[r] - m); sum += p0[r] + p1[r]; }
;                 lsum += sum;
;                 u32x4 pw[4];
; #pragma unroll
;                 for (int j = 0; j < 4; ++j) { pw[0][j] = pk_bf16(p0[2 * j], p0[2 * j + 1]); pw[1][j] = pk_bf16(p0[8 + 2 * j], p0[8 + 2 * j + 1]);
;                                               pw[2][j] = pk_bf16(p1[2 * j], p1[2 * j + 1]); pw[3][j] = pk_bf16(p1[8 + 2 * j], p1[8 + 2 * j + 1]); }
;                 const ATT_LAS unsigned char* vb = Vb + vlane;
; #pragma unroll
;                 for (int s = 0; s < 4; ++s) {
;                     const bf16x8 pa = __builtin_bit_cast(bf16x8, pw[s]);
;                     { const s16x4 lo = vtr(vb + s * 1024), h4 = vtr(vb + s * 1024 + 512);
;                       const bf16x8 vf = (bf16x8){lo[0], lo[1], lo[2], lo[3], h4[0], h4[1], h4[2], h4[3]};
;                       o0 = __builtin_amdgcn_mfma_f32_32x32x16_bf16(vf, pa, o0, 0, 0, 0); }
;                     { const s16x4 lo = vtr(vb + 4096 + s * 1024), h4 = vtr(vb + 4096 + s * 1024 + 512);
;                       const bf16x8 vf = (bf16x8){lo[0], lo[1], lo[2], lo[3], h4[0], h4[1], h4[2], h4[3]};
;                       o1 = __builtin_amdgcn_mfma_f32_32x32x16_bf16(vf, pa, o1, 0, 0, 0); }
;                 }
	v_add_f32_e32 v204, v80, v81
	v_add_f32_e32 v205, v82, v83
	v_add_f32_e32 v204, v204, v84
	v_add_f32_e32 v205, v205, v85
	v_add_f32_e32 v204, v204, v86
	v_add_f32_e32 v205, v205, v87
	v_add_f32_e32 v204, v204, v88
	v_add_f32_e32 v205, v205, v89
	v_add_f32_e32 v204, v204, v90
	v_add_f32_e32 v205, v205, v91
	v_add_f32_e32 v204, v204, v92
	v_add_f32_e32 v205, v205, v93
	v_add_f32_e32 v204, v204, v94
	v_add_f32_e32 v205, v205, v95
	v_add_f32_e32 v204, v204, v48
	v_add_f32_e32 v205, v205, v49
	v_add_f32_e32 v204, v204, v50
	v_add_f32_e32 v205, v205, v51
	v_add_f32_e32 v204, v204, v52
	v_add_f32_e32 v205, v205, v53
	v_add_f32_e32 v204, v204, v54
	v_add_f32_e32 v205, v205, v55
	v_add_f32_e32 v204, v204, v56
	v_add_f32_e32 v205, v205, v57
	v_add_f32_e32 v204, v204, v58
	v_add_f32_e32 v205, v205, v59
	v_add_f32_e32 v204, v204, v60
	v_add_f32_e32 v205, v205, v61
	v_add_f32_e32 v204, v204, v62
	v_add_f32_e32 v205, v205, v63
	v_add_f32_e32 v204, v204, v205
	v_add_f32_e32 v124, v124, v204
	v_cvt_pk_bf16_f32 v32, v80, v81
	v_cvt_pk_bf16_f32 v33, v82, v83
	v_cvt_pk_bf16_f32 v34, v84, v85
	v_cvt_pk_bf16_f32 v35, v86, v87
	v_cvt_pk_bf16_f32 v36, v88, v89
	v_cvt_pk_bf16_f32 v37, v90, v91
	v_cvt_pk_bf16_f32 v38, v92, v93
	v_cvt_pk_bf16_f32 v39, v94, v95
	v_cvt_pk_bf16_f32 v40, v48, v49
	v_cvt_pk_bf16_f32 v41, v50, v51
	v_cvt_pk_bf16_f32 v42, v52, v53
	v_cvt_pk_bf16_f32 v43, v54, v55
	v_cvt_pk_bf16_f32 v44, v56, v57
	v_cvt_pk_bf16_f32 v45, v58, v59
	v_cvt_pk_bf16_f32 v46, v60, v61
	v_cvt_pk_bf16_f32 v47, v62, v63
	s_nop 1
	s_waitcnt lgkmcnt(0)
	v_mfma_f32_32x32x16_bf16 v[0:15], v[160:163], v[32:35], v[0:15]
	v_mfma_f32_32x32x16_bf16 v[16:31], v[176:179], v[32:35], v[16:31]
	v_mfma_f32_32x32x16_bf16 v[0:15], v[164:167], v[36:39], v[0:15]
	v_mfma_f32_32x32x16_bf16 v[16:31], v[180:183], v[36:39], v[16:31]
	v_mfma_f32_32x32x16_bf16 v[0:15], v[168:171], v[40:43], v[0:15]
	v_mfma_f32_32x32x16_bf16 v[16:31], v[184:187], v[40:43], v[16:31]
	v_mfma_f32_32x32x16_bf16 v[0:15], v[172:175], v[44:47], v[0:15]
	v_mfma_f32_32x32x16_bf16 v[16:31], v[188:191], v[44:47], v[16:31]
	s_branch .Lmsk_tail
; #define ATT_LAS __attribute__((address_space(3)))
; __device__ __forceinline__ int crow(int r, int hi) { return (r & 3) + 8 * (r >> 2) + 4 * hi; }
; __device__ __forceinline__ void attn_unit(int uv, const float* sink_l, const bf16_t* P, bf16_t* Y, ATT_LAS unsigned char* lds, const float* rpb_l, const float* qn_l, const float* kn_l) {
;     ...
;             if (a.mode == 1) need = (tl * 64 + 63 >= qw - 128) && (tl * 64 <= qw + 31 + 128);
;             else { const int rs = clampi(qr - 4, 0, 120); need = (tl >= rs) && (tl < rs + 8); }
;             if (need) {
;                 const ATT_LAS unsigned char* Kb = ATT_KBUF(cur); const ATT_LAS unsigned char* Vb = ATT_VBUF(cur);
;                 f32x16 p0 = {}, p1 = {};
; #pragma unroll
;                 for (int d0 = 0; d0 < 4; ++d0) {
;                     const bf16x8 k0 = *(const ATT_LAS bf16x8*)(Kb + kfrag + d0 * 2048);
;                     const bf16x8 k1 = *(const ATT_LAS bf16x8*)(Kb + kfrag + d0 * 2048 + 512);
;                     p0 = __builtin_amdgcn_mfma_f32_32x32x16_bf16(k0, qf[d0], p0, 0, 0, 0);
;                     p1 = __builtin_amdgcn_mfma_f32_32x32x16_bf16(k1, qf[d0], p1, 0, 0, 0);
;                 }
;                 if (a.mode == 1) { const int dq = tl * 64 - (qw + r32);
; #pragma unroll
;                     for (int r = 0; r < 16; ++r) { const int d = dq + crow(r, hi); if (d > 128 || d < -128) p0[r] = NEGF; if (d + 32 > 128 || d + 32 < -128) p1[r] = NEGF; } }
;                 else { const int qc = 32 * (wid & 1) + r32, cs = clampi(qc - 8, 0, 48); const ATT_LAS float* trow = tbl + (tl - qr + 7) * 31 + 15 - qc;
; #pragma unroll
;                     for (int r = 0; r < 16; ++r) { const int kcl = crow(r, hi);
;                         const float b0 = trow[kcl], b1 = trow[kcl + 32];
;                         p0[r] = ((unsigned)(kcl - cs) < 16u) ? p0[r] + b0 : NEGF;
;                         p1[r] = ((unsigned)(kcl + 32 - cs) < 16u) ? p1[r] + b1 : NEGF; } }
;                 const float mt = rowmax32(p0, p1);
;                 if (__any(mt > m)) { const float mn = fmaxf(m, mt), alpha = __builtin_amdgcn_exp2f(m - mn); m = mn; lsum *= alpha;
.Lmk_lat:
	s_and_b64 vcc, exec, s[2:3]
	s_cbranch_vccz .Lmsk_win
	v_readfirstlane_b32 vcc_lo, v192
	s_nop 0
	s_bitcmp1_b32 vcc_lo, 6
	s_cbranch_scc1 .Lnb_odd
	ds_read2_b32 v[32:33], v127 offset1:1
	ds_read2_b32 v[34:35], v127 offset0:2 offset1:3
	ds_read2_b32 v[36:37], v127 offset0:8 offset1:9
	ds_read2_b32 v[38:39], v127 offset0:10 offset1:11
	ds_read2_b32 v[40:41], v127 offset0:16 offset1:17
	ds_read2_b32 v[42:43], v127 offset0:18 offset1:19
	ds_read2_b32 v[44:45], v127 offset0:24 offset1:25
	s_waitcnt lgkmcnt(14)
	v_mfma_f32_32x32x16_bf16 v[80:95], v[128:131], v[96:99], 0
	ds_read2_b32 v[46:47], v127 offset0:26 offset1:27
	s_waitcnt lgkmcnt(14)
	v_mfma_f32_32x32x16_bf16 v[48:63], v[132:135], v[96:99], 0
	ds_read2_b32 v[64:65], v127 offset0:32 offset1:33
	s_waitcnt lgkmcnt(14)
	v_mfma_f32_32x32x16_bf16 v[80:95], v[136:139], v[100:103], v[80:95]
	ds_read2_b32 v[66:67], v127 offset0:34 offset1:35
	s_waitcnt lgkmcnt(14)
	v_mfma_f32_32x32x16_bf16 v[48:63], v[140:143], v[100:103], v[48:63]
	ds_read_b64_tr_b16 v[160:161], v242 offset:24576
	s_waitcnt lgkmcnt(14)
	v_mfma_f32_32x32x16_bf16 v[80:95], v[144:147], v[104:107], v[80:95]
	ds_read_b64_tr_b16 v[162:163], v242 offset:25088
	s_waitcnt lgkmcnt(14)
	v_mfma_f32_32x32x16_bf16 v[48:63], v[148:151], v[104:107], v[48:63]
	ds_read_b64_tr_b16 v[176:177], v242 offset:28672
	s_waitcnt lgkmcnt(14)
	v_mfma_f32_32x32x16_bf16 v[80:95], v[152:155], v[108:111], v[80:95]
	ds_read_b64_tr_b16 v[178:179], v242 offset:29184
	s_waitcnt lgkmcnt(14)
	v_mfma_f32_32x32x16_bf16 v[48:63], v[156:159], v[108:111], v[48:63]
	ds_read_b64_tr_b16 v[164:165], v242 offset:25600
	s_waitcnt lgkmcnt(14)
	ds_read_b64_tr_b16 v[166:167], v242 offset:26112
	s_nop 5
	v_add_f32_e32 v32, v80, v32
	v_add_f32_e32 v33, v81, v33
	v_cndmask_b32_e64 v32, v216, v32, s[0:1]
	v_cndmask_b32_e64 v33, v216, v33, s[4:5]
	s_waitcnt lgkmcnt(14)
	ds_read_b64_tr_b16 v[180:181], v242 offset:29696
	v_add_f32_e32 v34, v82, v34
	v_add_f32_e32 v35, v83, v35
	v_cndmask_b32_e64 v34, v216, v34, s[10:11]
	v_cndmask_b32_e64 v35, v216, v35, s[14:15]
	s_waitcnt lgkmcnt(14)
	ds_read_b64_tr_b16 v[182:183], v242 offset:30208
	v_add_f32_e32 v36, v84, v36
	v_add_f32_e32 v37, v85, v37
	v_cndmask_b32_e64 v36, v216, v36, s[18:19]
	v_cndmask_b32_e64 v37, v216, v37, s[22:23]
	s_waitcnt lgkmcnt(14)
	ds_read_b64_tr_b16 v[168:169], v242 offset:26624
	v_add_f32_e32 v38, v86, v38
	v_add_f32_e32 v39, v87, v39
	v_cndmask_b32_e64 v38, v216, v38, s[26:27]
	v_cndmask_b32_e64 v39, v216, v39, s[30:31]
	s_waitcnt lgkmcnt(14)
	ds_read_b64_tr_b16 v[170:171], v242 offset:27136
	v_add_f32_e32 v40, v88, v40
	v_add_f32_e32 v41, v89, v41
	v_cndmask_b32_e64 v40, v216, v40, s[76:77]
	v_cndmask_b32_e64 v41, v216, v41, s[40:41]
	s_waitcnt lgkmcnt(14)
	ds_read_b64_tr_b16 v[184:185], v242 offset:30720
	v_add_f32_e32 v42, v90, v42
	v_add_f32_e32 v43, v91, v43
	v_cndmask_b32_e64 v42, v216, v42, s[44:45]
	v_cndmask_b32_e64 v43, v216, v43, s[48:49]
	s_waitcnt lgkmcnt(14)
	ds_read_b64_tr_b16 v[186:187], v242 offset:31232
	v_add_f32_e32 v44, v92, v44
	v_add_f32_e32 v45, v93, v45
	v_cndmask_b32_e64 v44, v216, v44, s[52:53]
	v_cndmask_b32_e64 v45, v216, v45, s[56:57]
	s_waitcnt lgkmcnt(14)
	v_add_f32_e32 v46, v94, v46
	v_add_f32_e32 v47, v95, v47
	v_cndmask_b32_e64 v46, v216, v46, s[60:61]
	v_cndmask_b32_e64 v47, v216, v47, s[64:65]
	s_waitcnt lgkmcnt(13)
	v_add_f32_e32 v64, v48, v64
	v_add_f32_e32 v65, v49, v65
	v_cndmask_b32_e64 v64, v216, v64, s[68:69]
	v_cndmask_b32_e64 v65, v216, v65, s[8:9]
	s_waitcnt lgkmcnt(12)
	v_add_f32_e32 v66, v50, v66
	v_add_f32_e32 v67, v51, v67
	v_cndmask_b32_e64 v66, v216, v66, s[12:13]
	v_cndmask_b32_e64 v67, v216, v67, s[16:17]
	v_max3_f32 v204, v32, v33, v34
	v_max3_f32 v205, v35, v36, v37
	v_max3_f32 v204, v204, v38, v39
	v_max3_f32 v205, v205, v40, v41
	v_max3_f32 v204, v204, v42, v43
	v_max3_f32 v205, v205, v44, v45
	v_max3_f32 v204, v204, v46, v47
	v_max3_f32 v205, v205, v64, v65
	v_max3_f32 v204, v204, v66, v67
	v_max_f32_e32 v204, v204, v205
	v_mov_b32_e32 v205, v204
	s_nop 1
	v_permlane32_swap_b32_e32 v204, v205
	v_max_f32_e32 v204, v204, v205
	v_cmp_gt_f32_e32 vcc, v204, v202
	s_cbranch_vccz .Lnb_even_norescale
	v_max_f32_e32 v205, v202, v204
	v_sub_f32_e32 v208, v202, v205
	v_exp_f32_e32 v208, v208
	v_mov_b32_e32 v202, v205
	v_pk_mul_f32 v[0:1], v[0:1], v[208:209] op_sel_hi:[1,0]
	v_pk_mul_f32 v[2:3], v[2:3], v[208:209] op_sel_hi:[1,0]
	v_pk_mul_f32 v[4:5], v[4:5], v[208:209] op_sel_hi:[1,0]
	v_pk_mul_f32 v[6:7], v[6:7], v[208:209] op_sel_hi:[1,0]
	v_pk_mul_f32 v[8:9], v[8:9], v[208:209] op_sel_hi:[1,0]
	v_pk_mul_f32 v[10:11], v[10:11], v[208:209] op_sel_hi:[1,0]
	v_pk_mul_f32 v[12:13], v[12:13], v[208:209] op_sel_hi:[1,0]
	v_pk_mul_f32 v[14:15], v[14:15], v[208:209] op_sel_hi:[1,0]
	v_pk_mul_f32 v[16:17], v[16:17], v[208:209] op_sel_hi:[1,0]
	v_pk_mul_f32 v[18:19], v[18:19], v[208:209] op_sel_hi:[1,0]
	v_pk_mul_f32 v[20:21], v[20:21], v[208:209] op_sel_hi:[1,0]
	v_pk_mul_f32 v[22:23], v[22:23], v[208:209] op_sel_hi:[1,0]
	v_pk_mul_f32 v[24:25], v[24:25], v[208:209] op_sel_hi:[1,0]
	v_pk_mul_f32 v[26:27], v[26:27], v[208:209] op_sel_hi:[1,0]
	v_pk_mul_f32 v[28:29], v[28:29], v[208:209] op_sel_hi:[1,0]
	v_pk_mul_f32 v[30:31], v[30:31], v[208:209] op_sel_hi:[1,0]
	v_mul_f32_e32 v124, v124, v208
